# split-phase seam 2 with thread-0 polling: S5 chunk states first, attention second, both only signal; phase 3 starts without the blocking seam (XCC-level mode)
# baseline (speedup 1.0000x reference)
.LBB0_203:
	s_cmp_gt_i32 s29, 2
	s_cselect_b64 s[0:1], -1, 0
	s_and_b64 s[4:5], s[6:7], s[0:1]
	s_andn2_b64 vcc, exec, s[4:5]
	s_cbranch_vccnz .LBB0_253
	v_mov_b32_e32 v149, 0x4000
	global_load_dwordx4 v[140:143], v149, s[70:71] sc1
	global_load_dwordx4 v[144:147], v149, s[70:71] offset:16 sc1
	s_waitcnt vmcnt(0)
	v_cmp_eq_u32_e32 vcc, 0, v196
	s_waitcnt lgkmcnt(0)
	s_barrier
	v_bcnt_u32_b32 v148, v140, 0
	v_bcnt_u32_b32 v148, v141, v148
	v_bcnt_u32_b32 v148, v142, v148
	v_bcnt_u32_b32 v148, v143, v148
	v_bcnt_u32_b32 v148, v144, v148
	v_bcnt_u32_b32 v148, v145, v148
	v_bcnt_u32_b32 v148, v146, v148
	v_bcnt_u32_b32 v148, v147, v148
	s_nop 0
	v_readfirstlane_b32 s100, v148
	s_cmp_eq_u32 s100, 8
	s_cselect_b32 s100, 1, 0
	s_and_saveexec_b64 s[4:5], vcc
	s_cbranch_execz .LBB0_252
	v_mov_b32_e32 v0, s94
	s_waitcnt vmcnt(0) expcnt(0) lgkmcnt(0)
	ds_read_b32 v2, v0
	ds_read_b32 v0, v0 offset:4
	s_waitcnt lgkmcnt(1)
	v_cmp_ne_u32_e32 vcc, 0, v2
	s_cbranch_vccnz .LBB0_220
	s_add_u32 s6, s70, 0x4200
	s_addc_u32 s7, s71, 0
	s_add_u32 s8, s70, 0x4400
	s_addc_u32 s9, s71, 0
	s_add_u32 s12, s70, 0x4500
	s_addc_u32 s13, s71, 0
	s_add_u32 s14, s70, 0x4600
	s_addc_u32 s15, s71, 0
	s_add_u32 s16, s70, 0x4700
	s_addc_u32 s17, s71, 0
	s_add_u32 s18, s70, 0x4800
	s_addc_u32 s19, s71, 0
	s_add_u32 s20, s70, 0x4900
	s_addc_u32 s21, s71, 0
	s_add_u32 s26, s70, 0x4a00
	s_addc_u32 s27, s71, 0
	s_add_u32 s36, s70, 0x4b00
	s_addc_u32 s37, s71, 0
	s_add_u32 s38, s70, 0x4c00
	s_addc_u32 s39, s71, 0
	s_add_u32 s40, s70, 0x4d00
	s_addc_u32 s41, s71, 0
	s_add_u32 s42, s70, 0x4e00
	s_addc_u32 s43, s71, 0
	s_add_u32 s44, s70, 0x4f00
	s_addc_u32 s45, s71, 0
	s_add_u32 s48, s70, 0x5000
	s_addc_u32 s49, s71, 0
	s_add_u32 s52, s70, 0x5100
	s_addc_u32 s53, s71, 0
	s_add_u32 s54, s70, 0x5200
	s_addc_u32 s55, s71, 0
	s_mul_i32 s3, s31, s95
	s_add_u32 s56, s70, 0x5300
	s_mul_i32 s3, s3, s30
	s_addc_u32 s57, s71, 0
	s_mov_b32 s10, 1
	v_mov_b32_e32 v16, 0
	s_branch .LBB0_208

.LBB0_253:
	s_cmp_lt_i32 s28, 3
	s_cselect_b64 s[4:5], -1, 0
	s_and_b64 s[6:7], s[4:5], s[0:1]
	v_mov_b32_e32 v197, v196
	s_andn2_b64 vcc, exec, s[6:7]
	s_cbranch_vccnz .LBB0_343
	s_branch .LBB0_334
.Lb_attn:
	v_readfirstlane_b32 s0, v196
	s_cmpk_lt_u32 s0, 0x100
	s_cbranch_scc1 .Lap_skip
	s_setprio 1

.Lb_ssma_done:
	s_waitcnt vmcnt(0) lgkmcnt(0)
	s_barrier
	v_readfirstlane_b32 s72, v196
	s_cmp_lt_u32 s72, 64
	s_cbranch_scc0 .Lb_a_skip
	s_lshl_b32 s72, s33, 8
	s_addk_i32 s72, 0x1408
	s_mov_b64 s[74:75], exec
	s_mov_b64 exec, 1
	v_mov_b32_e32 v30, s72
	v_mov_b32_e32 v31, 1
	global_atomic_add v30, v31, s[92:93]
	s_mov_b64 exec, s[74:75]
.Lb_a_skip:
	v_and_b32_e32 v139, 63, v196
	s_branch .Lb_attn
.Lb_attn_done:
	s_setprio 0
	v_readfirstlane_b32 s72, v196
	s_cmp_lt_u32 s72, 64
	s_cselect_b32 s73, 1, 0
	s_cbranch_scc0 .Lb_b1
	s_lshl_b32 s72, s33, 8
	s_addk_i32 s72, 0x1408
	s_mov_b64 s[74:75], exec
	s_mov_b64 exec, 1
	v_mov_b32_e32 v128, s72
	global_load_dword v129, v128, s[92:93] sc1
	v_mov_b32_e32 v130, s94
	ds_read_b32 v130, v130
	s_mov_b64 exec, s[74:75]
.Lb_b1:
	s_waitcnt vmcnt(0) lgkmcnt(0)
	s_barrier
	s_cmp_lg_u32 s73, 0
	s_cbranch_scc0 .Lb_b2
	s_mov_b64 s[74:75], exec
	s_mov_b64 exec, 1
	v_readfirstlane_b32 s101, v130
	s_mov_b32 s76, 0
.Lb_pa:
	v_readfirstlane_b32 s77, v129
	s_cmp_ge_u32 s77, s101
	s_cbranch_scc1 .Lb_pa_ok
	s_add_i32 s76, s76, 1
	s_cmp_gt_u32 s76, 0x4000
	s_cbranch_scc1 .Lb_pa_ok
	s_sleep 1
	global_load_dword v129, v128, s[92:93] sc1
	s_waitcnt vmcnt(0)
	s_branch .Lb_pa
.Lb_pa_ok:
	buffer_inv sc1
	v_add_u32_e32 v128, 4, v128
	v_mov_b32_e32 v129, 1
	global_atomic_add v128, v129, s[92:93]
	s_waitcnt vmcnt(0)
	s_mov_b64 exec, s[74:75]
.Lb_b2:
	s_barrier
.LBB0_343:
	s_cmp_gt_i32 s29, 3
	s_cselect_b64 s[0:1], -1, 0
	s_and_b64 s[4:5], s[6:7], s[0:1]
	s_andn2_b64 vcc, exec, s[4:5]
	s_cbranch_vccnz .LBB0_393
	s_cmp_lg_u32 s100, 0
	s_cbranch_scc1 .LBB0_393
	s_waitcnt vmcnt(0)
	v_cmp_eq_u32_e32 vcc, 0, v196
	s_waitcnt lgkmcnt(0)
	s_barrier
	s_and_saveexec_b64 s[4:5], vcc
	s_cbranch_execz .LBB0_392
	v_mov_b32_e32 v0, s94
	s_waitcnt vmcnt(0) expcnt(0) lgkmcnt(0)
	ds_read_b32 v2, v0
	ds_read_b32 v0, v0 offset:4
	s_waitcnt lgkmcnt(1)
	v_cmp_ne_u32_e32 vcc, 0, v2
	s_cbranch_vccnz .LBB0_360
	s_add_u32 s6, s70, 0x4200
	s_addc_u32 s7, s71, 0
	s_add_u32 s8, s70, 0x4400
	s_addc_u32 s9, s71, 0
	s_add_u32 s12, s70, 0x4500
	s_addc_u32 s13, s71, 0
	s_add_u32 s14, s70, 0x4600
	s_addc_u32 s15, s71, 0
	s_add_u32 s16, s70, 0x4700
	s_addc_u32 s17, s71, 0
	s_add_u32 s18, s70, 0x4800
	s_addc_u32 s19, s71, 0
	s_add_u32 s20, s70, 0x4900
	s_addc_u32 s21, s71, 0
	s_add_u32 s26, s70, 0x4a00
	s_addc_u32 s27, s71, 0
	s_add_u32 s36, s70, 0x4b00
	s_addc_u32 s37, s71, 0
	s_add_u32 s38, s70, 0x4c00
	s_addc_u32 s39, s71, 0
	s_add_u32 s40, s70, 0x4d00
	s_addc_u32 s41, s71, 0
	s_add_u32 s42, s70, 0x4e00
	s_addc_u32 s43, s71, 0
	s_add_u32 s44, s70, 0x4f00
	s_addc_u32 s45, s71, 0
	s_add_u32 s48, s70, 0x5000
	s_addc_u32 s49, s71, 0
	s_add_u32 s52, s70, 0x5100
	s_addc_u32 s53, s71, 0
	s_add_u32 s54, s70, 0x5200
	s_addc_u32 s55, s71, 0
	s_mul_i32 s3, s31, s95
	s_add_u32 s56, s70, 0x5300
	s_mul_i32 s3, s3, s30
	s_addc_u32 s57, s71, 0
	s_mov_b32 s10, 1
	v_mov_b32_e32 v16, 0
	s_branch .LBB0_348

.LBB0_395:
	s_or_b64 exec, exec, s[6:7]
	s_waitcnt lgkmcnt(0)
	s_barrier
	v_readfirstlane_b32 s72, v196
	s_cmp_lt_u32 s72, 64
	s_cbranch_scc0 .Lb_pb_skip1
	s_lshl_b32 s72, s33, 8
	s_addk_i32 s72, 0x140c
	s_mov_b64 s[74:75], exec
	s_mov_b64 exec, 1
	v_mov_b32_e32 v44, s72
	global_load_dword v45, v44, s[92:93] sc1
	s_mov_b64 exec, s[74:75]
.Lb_pb_skip1:
	ds_read2st64_b32 v[32:33], v208 offset1:1
	ds_read2st64_b32 v[34:35], v208 offset0:2 offset1:3
	ds_read2st64_b32 v[36:37], v208 offset0:4 offset1:5
	ds_read2st64_b32 v[38:39], v208 offset0:6 offset1:7
	s_waitcnt lgkmcnt(3)
	v_add_f32_e32 v32, 0, v32
	v_add_f32_e32 v32, v32, v33
	s_waitcnt lgkmcnt(2)
	v_add_f32_e32 v32, v32, v34
	v_add_f32_e32 v32, v32, v35
	s_waitcnt lgkmcnt(1)
	v_add_f32_e32 v32, v32, v36
	v_add_f32_e32 v32, v32, v37
	s_waitcnt lgkmcnt(0)
	v_add_f32_e32 v32, v32, v38
	v_add_f32_e32 v32, v32, v39
	v_fmamk_f32 v32, v32, 0x3b000000, v221
	v_mul_f32_e32 v33, 0x4f800000, v32
	v_cmp_gt_f32_e32 vcc, s43, v32
	s_nop 1
	v_cndmask_b32_e32 v32, v32, v33, vcc
	v_sqrt_f32_e32 v33, v32
	s_nop 0
	v_add_u32_e32 v34, -1, v33
	v_fma_f32 v35, -v34, v33, v32
	v_cmp_ge_f32_e64 s[6:7], 0, v35
	v_add_u32_e32 v35, 1, v33
	s_nop 0
	v_cndmask_b32_e64 v34, v33, v34, s[6:7]
	v_fma_f32 v33, -v35, v33, v32
	v_cmp_lt_f32_e64 s[6:7], 0, v33
	s_nop 1
	v_cndmask_b32_e64 v33, v34, v35, s[6:7]
	v_mul_f32_e32 v34, 0x37800000, v33
	v_cndmask_b32_e32 v33, v33, v34, vcc
	v_cmp_class_f32_e32 vcc, v32, v222
	s_nop 1
	v_cndmask_b32_e32 v32, v33, v32, vcc
	v_div_scale_f32 v33, s[6:7], v32, v32, 1.0
	v_rcp_f32_e32 v34, v33
	s_nop 0
	v_fma_f32 v35, -v33, v34, 1.0
	v_fmac_f32_e32 v34, v35, v34
	v_div_scale_f32 v35, vcc, 1.0, v32, 1.0
	v_mul_f32_e32 v36, v35, v34
	v_fma_f32 v37, -v33, v36, v35
	v_fmac_f32_e32 v36, v37, v34
	v_fma_f32 v33, -v33, v36, v35
	v_div_fmas_f32 v33, v33, v34, v36
	v_div_fixup_f32 v36, v33, v32, 1.0
	v_mul_f32_e32 v34, v76, v36
	v_mul_f32_e32 v35, v77, v36
	v_lshlrev_b64 v[32:33], 11, v[192:193]
	v_cvt_pk_bf16_f32 v34, v34, v35
	v_mul_f32_e32 v35, v74, v36
	v_readfirstlane_b32 s72, v196
	s_cmp_lt_u32 s72, 64
	s_cbranch_scc0 .Lb_pb_skip2
	s_mov_b64 s[74:75], exec
	s_mov_b64 exec, 1
	s_mov_b32 s76, 0
	s_waitcnt vmcnt(0)
.Lb_pb:
	v_readfirstlane_b32 s77, v45
	s_cmp_ge_u32 s77, s101
	s_cbranch_scc1 .Lb_pb_ok
	s_add_i32 s76, s76, 1
	s_cmp_gt_u32 s76, 0x4000
	s_cbranch_scc1 .Lb_pb_ok
	s_sleep 1
	global_load_dword v45, v44, s[92:93] sc1
	s_waitcnt vmcnt(0)
	s_branch .Lb_pb
.Lb_pb_ok:
	buffer_inv sc1
	s_mov_b64 exec, s[74:75]
.Lb_pb_skip2:
	v_lshl_add_u64 v[32:33], v[182:183], 0, v[32:33]
	v_mul_f32_e32 v37, v75, v36
	v_cvt_pk_bf16_f32 v35, v35, v37
	global_store_dwordx2 v[32:33], v[34:35], off offset:1024
	v_mul_f32_e32 v34, v72, v36
	v_mul_f32_e32 v35, v73, v36
	v_cvt_pk_bf16_f32 v34, v34, v35
	v_mul_f32_e32 v35, v70, v36
	v_mul_f32_e32 v37, v71, v36
	v_cvt_pk_bf16_f32 v35, v35, v37
	global_store_dwordx2 v[32:33], v[34:35], off offset:1056
	v_mul_f32_e32 v34, v68, v36
	v_mul_f32_e32 v35, v69, v36
	v_cvt_pk_bf16_f32 v34, v34, v35
	v_mul_f32_e32 v35, v78, v36
	v_mul_f32_e32 v37, v79, v36
	v_cvt_pk_bf16_f32 v35, v35, v37
	global_store_dwordx2 v[32:33], v[34:35], off offset:1088
	v_mul_f32_e32 v34, v64, v36
	v_mul_f32_e32 v35, v65, v36
	v_cvt_pk_bf16_f32 v34, v34, v35
	v_mul_f32_e32 v35, v66, v36
	v_mul_f32_e32 v36, v67, v36
	v_cvt_pk_bf16_f32 v35, v35, v36
	ds_read2st64_b32 v[36:37], v209 offset1:1
	ds_read2st64_b32 v[38:39], v209 offset0:2 offset1:3
	ds_read2st64_b32 v[40:41], v209 offset0:4 offset1:5
	ds_read2st64_b32 v[42:43], v209 offset0:6 offset1:7
	global_store_dwordx2 v[32:33], v[34:35], off offset:1120
	s_waitcnt lgkmcnt(3)
	v_add_f32_e32 v36, 0, v36
	v_add_f32_e32 v36, v36, v37
	s_waitcnt lgkmcnt(2)
	v_add_f32_e32 v36, v36, v38
	v_add_f32_e32 v36, v36, v39
	s_waitcnt lgkmcnt(1)
	v_add_f32_e32 v36, v36, v40
	v_add_f32_e32 v36, v36, v41
	s_waitcnt lgkmcnt(0)
	v_add_f32_e32 v36, v36, v42
	v_add_f32_e32 v36, v36, v43
	v_fmamk_f32 v36, v36, 0x3b000000, v221
	v_mul_f32_e32 v37, 0x4f800000, v36
	v_cmp_gt_f32_e32 vcc, s43, v36
	s_nop 1
	v_cndmask_b32_e32 v36, v36, v37, vcc
	v_sqrt_f32_e32 v37, v36
	s_nop 0
	v_add_u32_e32 v38, -1, v37
	v_fma_f32 v39, -v38, v37, v36
	v_cmp_ge_f32_e64 s[6:7], 0, v39
	v_add_u32_e32 v39, 1, v37
	s_nop 0
	v_cndmask_b32_e64 v38, v37, v38, s[6:7]
	v_fma_f32 v37, -v39, v37, v36
	v_cmp_lt_f32_e64 s[6:7], 0, v37
	s_nop 1
	v_cndmask_b32_e64 v37, v38, v39, s[6:7]
	v_mul_f32_e32 v38, 0x37800000, v37
	v_cndmask_b32_e32 v37, v37, v38, vcc
	v_cmp_class_f32_e32 vcc, v36, v222
	s_nop 1
	v_cndmask_b32_e32 v36, v37, v36, vcc
	v_div_scale_f32 v37, s[6:7], v36, v36, 1.0
	v_rcp_f32_e32 v38, v37
	s_nop 0
	v_fma_f32 v32, -v37, v38, 1.0
	v_fmac_f32_e32 v38, v32, v38
	v_div_scale_f32 v32, vcc, 1.0, v36, 1.0
	v_mul_f32_e32 v33, v32, v38
	v_fma_f32 v34, -v37, v33, v32
	v_fmac_f32_e32 v33, v34, v38
	v_fma_f32 v32, -v37, v33, v32
	v_div_fmas_f32 v32, v32, v38, v33
	v_div_fixup_f32 v36, v32, v36, 1.0
	v_mul_f32_e32 v34, v60, v36
	v_mul_f32_e32 v35, v61, v36
	v_lshlrev_b64 v[32:33], 11, v[190:191]
	v_cvt_pk_bf16_f32 v34, v34, v35
	v_mul_f32_e32 v35, v62, v36
	v_lshl_add_u64 v[32:33], v[182:183], 0, v[32:33]
	v_mul_f32_e32 v37, v63, v36
	v_cvt_pk_bf16_f32 v35, v35, v37
	global_store_dwordx2 v[32:33], v[34:35], off offset:1024
	v_mul_f32_e32 v34, v56, v36
	v_mul_f32_e32 v35, v57, v36
	v_cvt_pk_bf16_f32 v34, v34, v35
	v_mul_f32_e32 v35, v58, v36
	v_mul_f32_e32 v37, v59, v36
	v_cvt_pk_bf16_f32 v35, v35, v37
	global_store_dwordx2 v[32:33], v[34:35], off offset:1056
	v_mul_f32_e32 v34, v52, v36
	v_mul_f32_e32 v35, v53, v36
	v_cvt_pk_bf16_f32 v34, v34, v35
	v_mul_f32_e32 v35, v54, v36
	v_mul_f32_e32 v37, v55, v36
	v_cvt_pk_bf16_f32 v35, v35, v37
	global_store_dwordx2 v[32:33], v[34:35], off offset:1088
	v_mul_f32_e32 v34, v48, v36
	v_mul_f32_e32 v35, v49, v36
	v_cvt_pk_bf16_f32 v34, v34, v35
	v_mul_f32_e32 v35, v50, v36
	v_mul_f32_e32 v36, v51, v36
	v_cvt_pk_bf16_f32 v35, v35, v36
	ds_read2st64_b32 v[36:37], v210 offset1:1
	ds_read2st64_b32 v[38:39], v210 offset0:2 offset1:3
	ds_read2st64_b32 v[40:41], v210 offset0:4 offset1:5
	ds_read2st64_b32 v[42:43], v210 offset0:6 offset1:7
	global_store_dwordx2 v[32:33], v[34:35], off offset:1120
	s_waitcnt lgkmcnt(3)
	v_add_f32_e32 v36, 0, v36
	v_add_f32_e32 v36, v36, v37
	s_waitcnt lgkmcnt(2)
	v_add_f32_e32 v36, v36, v38
	v_add_f32_e32 v36, v36, v39
	s_waitcnt lgkmcnt(1)
	v_add_f32_e32 v36, v36, v40
	v_add_f32_e32 v36, v36, v41
	s_waitcnt lgkmcnt(0)
	v_add_f32_e32 v36, v36, v42
	v_add_f32_e32 v36, v36, v43
	v_fmamk_f32 v36, v36, 0x3b000000, v221
	v_mul_f32_e32 v37, 0x4f800000, v36
	v_cmp_gt_f32_e32 vcc, s43, v36
	s_nop 1
	v_cndmask_b32_e32 v36, v36, v37, vcc
	v_sqrt_f32_e32 v37, v36
	s_nop 0
	v_add_u32_e32 v38, -1, v37
	v_fma_f32 v39, -v38, v37, v36
	v_cmp_ge_f32_e64 s[6:7], 0, v39
	v_add_u32_e32 v39, 1, v37
	s_nop 0
	v_cndmask_b32_e64 v38, v37, v38, s[6:7]
	v_fma_f32 v37, -v39, v37, v36
	v_cmp_lt_f32_e64 s[6:7], 0, v37
	s_nop 1
	v_cndmask_b32_e64 v37, v38, v39, s[6:7]
	v_mul_f32_e32 v38, 0x37800000, v37
	v_cndmask_b32_e32 v37, v37, v38, vcc
	v_cmp_class_f32_e32 vcc, v36, v222
	s_nop 1
	v_cndmask_b32_e32 v36, v37, v36, vcc
	v_div_scale_f32 v37, s[6:7], v36, v36, 1.0
	v_rcp_f32_e32 v38, v37
	s_nop 0
	v_fma_f32 v32, -v37, v38, 1.0
	v_fmac_f32_e32 v38, v32, v38
	v_div_scale_f32 v32, vcc, 1.0, v36, 1.0
	v_mul_f32_e32 v33, v32, v38
	v_fma_f32 v34, -v37, v33, v32
	v_fmac_f32_e32 v33, v34, v38
	v_fma_f32 v32, -v37, v33, v32
	v_div_fmas_f32 v32, v32, v38, v33
	v_div_fixup_f32 v34, v32, v36, 1.0
	v_lshlrev_b64 v[32:33], 11, v[188:189]
	v_mul_f32_e32 v28, v28, v34
	v_mul_f32_e32 v29, v29, v34
	v_lshl_add_u64 v[32:33], v[182:183], 0, v[32:33]
	v_cvt_pk_bf16_f32 v28, v28, v29
	v_mul_f32_e32 v29, v30, v34
	v_mul_f32_e32 v24, v24, v34
	v_mul_f32_e32 v25, v25, v34
	v_mul_f32_e32 v30, v31, v34
	v_cvt_pk_bf16_f32 v29, v29, v30
	global_store_dwordx2 v[32:33], v[28:29], off offset:1024
	v_cvt_pk_bf16_f32 v24, v24, v25
	v_mul_f32_e32 v25, v26, v34
	v_mul_f32_e32 v20, v20, v34
	v_mul_f32_e32 v21, v21, v34
	v_mul_f32_e32 v26, v27, v34
	v_cvt_pk_bf16_f32 v25, v25, v26
	global_store_dwordx2 v[32:33], v[24:25], off offset:1056
	v_cvt_pk_bf16_f32 v20, v20, v21
	v_mul_f32_e32 v21, v22, v34
	v_mul_f32_e32 v16, v16, v34
	v_mul_f32_e32 v17, v17, v34
	v_mul_f32_e32 v22, v23, v34
	v_cvt_pk_bf16_f32 v21, v21, v22
	global_store_dwordx2 v[32:33], v[20:21], off offset:1088
	v_cvt_pk_bf16_f32 v16, v16, v17
	v_mul_f32_e32 v17, v18, v34
	v_mul_f32_e32 v18, v19, v34
	v_cvt_pk_bf16_f32 v17, v17, v18
	ds_read2st64_b32 v[18:19], v211 offset1:1
	ds_read2st64_b32 v[20:21], v211 offset0:2 offset1:3
	ds_read2st64_b32 v[22:23], v211 offset0:4 offset1:5
	ds_read2st64_b32 v[24:25], v211 offset0:6 offset1:7
	global_store_dwordx2 v[32:33], v[16:17], off offset:1120
	s_waitcnt lgkmcnt(3)
	v_add_f32_e32 v18, 0, v18
	v_add_f32_e32 v18, v18, v19
	s_waitcnt lgkmcnt(2)
	v_add_f32_e32 v18, v18, v20
	v_add_f32_e32 v18, v18, v21
	s_waitcnt lgkmcnt(1)
	v_add_f32_e32 v18, v18, v22
	v_add_f32_e32 v18, v18, v23
	s_waitcnt lgkmcnt(0)
	v_add_f32_e32 v18, v18, v24
	v_add_f32_e32 v18, v18, v25
	v_fmamk_f32 v18, v18, 0x3b000000, v221
	v_mul_f32_e32 v19, 0x4f800000, v18
	v_cmp_gt_f32_e32 vcc, s43, v18
	s_nop 1
	v_cndmask_b32_e32 v18, v18, v19, vcc
	v_sqrt_f32_e32 v19, v18
	s_nop 0
	v_add_u32_e32 v20, -1, v19
	v_fma_f32 v21, -v20, v19, v18
	v_cmp_ge_f32_e64 s[6:7], 0, v21
	v_add_u32_e32 v21, 1, v19
	s_nop 0
	v_cndmask_b32_e64 v20, v19, v20, s[6:7]
	v_fma_f32 v19, -v21, v19, v18
	v_cmp_lt_f32_e64 s[6:7], 0, v19
	s_nop 1
	v_cndmask_b32_e64 v19, v20, v21, s[6:7]
	v_mul_f32_e32 v20, 0x37800000, v19
	v_cndmask_b32_e32 v19, v19, v20, vcc
	v_cmp_class_f32_e32 vcc, v18, v222
	s_nop 1
	v_cndmask_b32_e32 v18, v19, v18, vcc
	v_div_scale_f32 v19, s[6:7], v18, v18, 1.0
	v_rcp_f32_e32 v20, v19
	s_add_u32 s6, s36, s42
	s_addc_u32 s7, s37, 0
	s_lshl_b64 s[6:7], s[6:7], 11
	v_fma_f32 v16, -v19, v20, 1.0
	v_fmac_f32_e32 v20, v16, v20
	v_div_scale_f32 v16, vcc, 1.0, v18, 1.0
	v_mul_f32_e32 v17, v16, v20
	v_fma_f32 v21, -v19, v17, v16
	v_fmac_f32_e32 v17, v21, v20
	v_fma_f32 v16, -v19, v17, v16
	v_div_fmas_f32 v16, v16, v20, v17
	v_div_fixup_f32 v18, v16, v18, 1.0
	v_lshlrev_b64 v[16:17], 11, v[186:187]
	v_mul_f32_e32 v12, v12, v18
	v_mul_f32_e32 v13, v13, v18
	v_lshl_add_u64 v[16:17], v[182:183], 0, v[16:17]
	v_cvt_pk_bf16_f32 v12, v12, v13
	v_mul_f32_e32 v13, v14, v18
	v_mul_f32_e32 v4, v4, v18
	v_mul_f32_e32 v5, v5, v18
	v_mul_f32_e32 v14, v15, v18
	v_cvt_pk_bf16_f32 v13, v13, v14
	global_store_dwordx2 v[16:17], v[12:13], off offset:1024
	v_cvt_pk_bf16_f32 v4, v4, v5
	v_mul_f32_e32 v5, v6, v18
	v_mul_f32_e32 v6, v7, v18
	v_cvt_pk_bf16_f32 v5, v5, v6
	global_store_dwordx2 v[16:17], v[4:5], off offset:1056
	v_mul_f32_e32 v4, v8, v18
	v_mul_f32_e32 v5, v9, v18
	v_cvt_pk_bf16_f32 v4, v4, v5
	v_mul_f32_e32 v5, v10, v18
	v_mul_f32_e32 v0, v0, v18
	v_mul_f32_e32 v1, v1, v18
	v_mul_f32_e32 v6, v11, v18
	v_cvt_pk_bf16_f32 v5, v5, v6
	global_store_dwordx2 v[16:17], v[4:5], off offset:1088
	v_cvt_pk_bf16_f32 v0, v0, v1
	v_mul_f32_e32 v1, v2, v18
	v_mul_f32_e32 v2, v3, v18
	v_cvt_pk_bf16_f32 v1, v1, v2
	global_store_dwordx2 v[16:17], v[0:1], off offset:1120
	v_lshl_add_u64 v[26:27], v[178:179], 0, s[6:7]
	s_waitcnt vmcnt(16)
	s_barrier
	global_load_dwordx4 v[0:3], v[26:27], off
	global_load_dwordx4 v[28:31], v[26:27], off offset:2048
	v_add_co_u32_e32 v24, vcc, s44, v26
	v_add_co_u32_e64 v20, s[6:7], s46, v26
	s_nop 0
	v_addc_co_u32_e32 v25, vcc, 0, v27, vcc
	v_add_co_u32_e32 v22, vcc, s45, v26
	v_addc_co_u32_e64 v21, s[6:7], 0, v27, s[6:7]
	s_nop 0
	v_addc_co_u32_e32 v23, vcc, 0, v27, vcc
	global_load_dwordx4 v[12:15], v[22:23], off
	global_load_dwordx4 v[8:11], v[22:23], off offset:2048
	s_add_i32 s50, s50, s30
	s_add_i32 s49, s49, 1
	s_add_i32 s48, s48, s30
	s_cmpk_lt_i32 s50, 0x100
	s_waitcnt vmcnt(3)
	v_lshlrev_b32_e32 v37, 16, v1
	v_lshlrev_b32_e32 v36, 16, v0
	v_and_b32_e32 v39, 0xffff0000, v1
	v_and_b32_e32 v38, 0xffff0000, v0
	v_pk_mul_f32 v[0:1], v[36:37], v[36:37]
	v_pk_mul_f32 v[4:5], v[38:39], v[38:39]
	v_lshlrev_b32_e32 v41, 16, v3
	v_add_f32_e32 v0, v0, v4
	v_add_f32_e32 v0, v1, v0
	v_lshlrev_b32_e32 v40, 16, v2
	v_and_b32_e32 v43, 0xffff0000, v3
	v_add_f32_e32 v0, v5, v0
	v_and_b32_e32 v42, 0xffff0000, v2
	v_mov_b32_e32 v2, v43
	v_mov_b32_e32 v3, v41
	v_fmac_f32_e32 v0, v40, v40
	v_pk_mul_f32 v[2:3], v[2:3], v[2:3]
	v_fmac_f32_e32 v0, v42, v42
	v_add_f32_e32 v0, v3, v0
	v_add_f32_e32 v0, v2, v0
	ds_bpermute_b32 v1, v212, v0
	s_waitcnt vmcnt(2)
	v_lshlrev_b32_e32 v51, 16, v31
	v_lshlrev_b32_e32 v50, 16, v30
	v_and_b32_e32 v53, 0xffff0000, v31
	v_and_b32_e32 v52, 0xffff0000, v30
	s_waitcnt lgkmcnt(0)
	v_add_f32_e32 v0, v0, v1
	ds_bpermute_b32 v1, v213, v0
	v_mov_b32_e32 v30, v53
	v_mov_b32_e32 v31, v51
	v_pk_mul_f32 v[30:31], v[30:31], v[30:31]
	s_waitcnt lgkmcnt(0)
	v_add_f32_e32 v0, v0, v1
	ds_bpermute_b32 v1, v214, v0
	s_waitcnt lgkmcnt(0)
	v_add_f32_e32 v0, v0, v1
	ds_bpermute_b32 v1, v215, v0
	s_waitcnt lgkmcnt(0)
	v_add_f32_e32 v0, v0, v1
	ds_bpermute_b32 v1, v197, v0
	s_waitcnt lgkmcnt(0)
	v_add_f32_e32 v0, v0, v1
	ds_bpermute_b32 v1, v149, v0
	s_waitcnt lgkmcnt(0)
	v_add_f32_e32 v0, v0, v1
	v_fmamk_f32 v0, v0, 0x3b000000, v221
	v_mul_f32_e32 v1, 0x4f800000, v0
	v_cmp_gt_f32_e32 vcc, s43, v0
	s_nop 1
	v_cndmask_b32_e32 v0, v0, v1, vcc
	v_sqrt_f32_e32 v1, v0
	s_nop 0
	v_add_u32_e32 v2, -1, v1
	v_fma_f32 v3, -v2, v1, v0
	v_cmp_ge_f32_e64 s[6:7], 0, v3
	v_add_u32_e32 v3, 1, v1
	s_nop 0
	v_cndmask_b32_e64 v2, v1, v2, s[6:7]
	v_fma_f32 v1, -v3, v1, v0
	v_cmp_lt_f32_e64 s[6:7], 0, v1
	s_nop 1
	v_cndmask_b32_e64 v1, v2, v3, s[6:7]
	v_mul_f32_e32 v2, 0x37800000, v1
	v_cndmask_b32_e32 v1, v1, v2, vcc
	v_cmp_class_f32_e32 vcc, v0, v222
	s_nop 1
	v_cndmask_b32_e32 v54, v1, v0, vcc
	v_div_scale_f32 v44, s[6:7], v54, v54, 1.0
	v_rcp_f32_e32 v45, v44
	global_load_dwordx4 v[16:19], v[24:25], off offset:2048
	global_load_dwordx4 v[4:7], v[20:21], off
	global_load_dwordx4 v[32:35], v[22:23], off offset:-4096
	global_load_dwordx4 v[0:3], v[20:21], off offset:2048
	v_fma_f32 v46, -v44, v45, 1.0
	v_fmac_f32_e32 v45, v46, v45
	v_div_scale_f32 v46, vcc, 1.0, v54, 1.0
	v_mul_f32_e32 v47, v46, v45
	v_fma_f32 v48, -v44, v47, v46
	v_fmac_f32_e32 v47, v48, v45
	v_fma_f32 v44, -v44, v47, v46
	v_div_fmas_f32 v55, v44, v45, v47
	v_lshlrev_b32_e32 v45, 16, v29
	v_lshlrev_b32_e32 v44, 16, v28
	v_and_b32_e32 v47, 0xffff0000, v29
	v_and_b32_e32 v46, 0xffff0000, v28
	v_pk_mul_f32 v[28:29], v[44:45], v[44:45]
	v_pk_mul_f32 v[48:49], v[46:47], v[46:47]
	s_nop 0
	v_add_f32_e32 v28, v28, v48
	v_add_f32_e32 v28, v29, v28
	v_add_f32_e32 v28, v49, v28
	v_fmac_f32_e32 v28, v50, v50
	v_fmac_f32_e32 v28, v52, v52
	v_add_f32_e32 v28, v31, v28
	v_add_f32_e32 v29, v30, v28
	ds_bpermute_b32 v48, v212, v29
	v_div_fixup_f32 v28, v55, v54, 1.0
	v_pk_mul_f32 v[30:31], v[28:29], v[36:37] op_sel_hi:[0,1]
	v_pk_mul_f32 v[36:37], v[28:29], v[38:39] op_sel_hi:[0,1]
	v_pk_mul_f32 v[38:39], v[28:29], v[40:41] op_sel_hi:[0,1]
	s_waitcnt lgkmcnt(0)
	v_add_f32_e32 v40, v29, v48
	ds_bpermute_b32 v41, v213, v40
	v_pk_mul_f32 v[28:29], v[28:29], v[42:43] op_sel_hi:[0,1]
	v_bfe_u32 v43, v28, 16, 1
	v_add3_u32 v28, v28, v43, s47
	v_bfe_u32 v43, v31, 16, 1
	s_waitcnt lgkmcnt(0)
	v_add_f32_e32 v40, v40, v41
	ds_bpermute_b32 v41, v214, v40
	v_bfe_u32 v42, v29, 16, 1
	v_bfe_u32 v48, v37, 16, 1
	v_add3_u32 v31, v31, v43, s47
	v_add3_u32 v37, v37, v48, s47
	s_waitcnt lgkmcnt(0)
	v_add_f32_e32 v40, v40, v41
	ds_bpermute_b32 v41, v215, v40
	v_add3_u32 v29, v29, v42, s47
	v_bfe_u32 v42, v30, 16, 1
	v_bfe_u32 v48, v38, 16, 1
	v_lshrrev_b32_e32 v43, 16, v31
	s_waitcnt lgkmcnt(0)
	v_add_f32_e32 v40, v40, v41
	ds_bpermute_b32 v41, v197, v40
	v_add3_u32 v38, v38, v48, s47
	v_add3_u32 v30, v30, v42, s47
	v_lshrrev_b32_e32 v42, 16, v30
	v_lshrrev_b32_e32 v30, 16, v38
	s_waitcnt lgkmcnt(0)
	v_add_f32_e32 v40, v40, v41
	ds_bpermute_b32 v41, v149, v40
	v_bfe_u32 v49, v36, 16, 1
	v_add3_u32 v36, v36, v49, s47
	v_bfe_u32 v49, v39, 16, 1
	v_add3_u32 v39, v39, v49, s47
	s_waitcnt lgkmcnt(0)
	v_add_f32_e32 v31, v40, v41
	v_fmamk_f32 v31, v31, 0x3b000000, v221
	v_mul_f32_e32 v38, 0x4f800000, v31
	v_cmp_gt_f32_e32 vcc, s43, v31
	v_and_or_b32 v30, v28, s19, v30
	s_nop 0
	v_cndmask_b32_e32 v38, v31, v38, vcc
	v_sqrt_f32_e32 v40, v38
	v_lshrrev_b32_e32 v31, 16, v39
	v_and_or_b32 v31, v29, s19, v31
	v_add_u32_e32 v28, -1, v40
	v_fma_f32 v29, -v28, v40, v38
	v_cmp_ge_f32_e64 s[6:7], 0, v29
	v_add_u32_e32 v29, 1, v40
	v_fma_f32 v39, -v29, v40, v38
	v_cndmask_b32_e64 v28, v40, v28, s[6:7]
	v_cmp_lt_f32_e64 s[6:7], 0, v39
	s_nop 1
	v_cndmask_b32_e64 v28, v28, v29, s[6:7]
	v_mul_f32_e32 v29, 0x37800000, v28
	v_cndmask_b32_e32 v28, v28, v29, vcc
	v_cmp_class_f32_e32 vcc, v38, v222
	v_and_or_b32 v29, v37, s19, v43
	s_waitcnt vmcnt(1)
	v_lshlrev_b32_e32 v37, 16, v33
	v_cndmask_b32_e32 v48, v28, v38, vcc
	v_div_scale_f32 v38, s[6:7], v48, v48, 1.0
	v_rcp_f32_e32 v39, v38
	v_and_or_b32 v28, v36, s19, v42
	global_store_dwordx4 v[26:27], v[28:31], off
	v_lshlrev_b32_e32 v36, 16, v32
	v_and_b32_e32 v33, 0xffff0000, v33
	v_fma_f32 v28, -v38, v39, 1.0
	v_fmac_f32_e32 v39, v28, v39
	v_div_scale_f32 v28, vcc, 1.0, v48, 1.0
	v_mul_f32_e32 v29, v28, v39
	v_fma_f32 v30, -v38, v29, v28
	v_fmac_f32_e32 v29, v30, v39
	v_fma_f32 v28, -v38, v29, v28
	v_and_b32_e32 v32, 0xffff0000, v32
	v_div_fmas_f32 v42, v28, v39, v29
	v_pk_mul_f32 v[28:29], v[36:37], v[36:37]
	v_pk_mul_f32 v[30:31], v[32:33], v[32:33]
	v_lshlrev_b32_e32 v39, 16, v35
	v_add_f32_e32 v28, v28, v30
	v_add_f32_e32 v28, v29, v28
	v_lshlrev_b32_e32 v38, 16, v34
	v_and_b32_e32 v35, 0xffff0000, v35
	v_add_f32_e32 v28, v31, v28
	v_and_b32_e32 v34, 0xffff0000, v34
	v_mov_b32_e32 v40, v35
	v_mov_b32_e32 v41, v39
	v_fmac_f32_e32 v28, v38, v38
	v_pk_mul_f32 v[40:41], v[40:41], v[40:41]
	v_fmac_f32_e32 v28, v34, v34
	v_add_f32_e32 v28, v41, v28
	v_add_f32_e32 v29, v40, v28
	ds_bpermute_b32 v49, v212, v29
	v_div_fixup_f32 v28, v42, v48, 1.0
	v_pk_mul_f32 v[30:31], v[28:29], v[44:45] op_sel_hi:[0,1]
	v_pk_mul_f32 v[40:41], v[28:29], v[46:47] op_sel_hi:[0,1]
	v_pk_mul_f32 v[42:43], v[28:29], v[50:51] op_sel_hi:[0,1]
	s_waitcnt lgkmcnt(0)
	v_add_f32_e32 v44, v29, v49
	ds_bpermute_b32 v45, v213, v44
	v_pk_mul_f32 v[28:29], v[28:29], v[52:53] op_sel_hi:[0,1]
	v_bfe_u32 v47, v28, 16, 1
	v_add3_u32 v28, v28, v47, s47
	v_bfe_u32 v47, v31, 16, 1
	s_waitcnt lgkmcnt(0)
	v_add_f32_e32 v44, v44, v45
	ds_bpermute_b32 v45, v214, v44
	v_bfe_u32 v46, v29, 16, 1
	v_bfe_u32 v48, v41, 16, 1
	v_add3_u32 v31, v31, v47, s47
	v_add3_u32 v41, v41, v48, s47
	s_waitcnt lgkmcnt(0)
	v_add_f32_e32 v44, v44, v45
	ds_bpermute_b32 v45, v215, v44
	v_add3_u32 v29, v29, v46, s47
	v_bfe_u32 v46, v30, 16, 1
	v_bfe_u32 v48, v42, 16, 1
	v_lshrrev_b32_e32 v47, 16, v31
	s_waitcnt lgkmcnt(0)
	v_add_f32_e32 v44, v44, v45
	ds_bpermute_b32 v45, v197, v44
	v_add3_u32 v42, v42, v48, s47
	v_add3_u32 v30, v30, v46, s47
	v_lshrrev_b32_e32 v46, 16, v30
	v_lshrrev_b32_e32 v30, 16, v42
	s_waitcnt lgkmcnt(0)
	v_add_f32_e32 v44, v44, v45
	ds_bpermute_b32 v45, v149, v44
	v_bfe_u32 v49, v40, 16, 1
	v_add3_u32 v40, v40, v49, s47
	v_bfe_u32 v49, v43, 16, 1
	v_add3_u32 v43, v43, v49, s47
	s_waitcnt lgkmcnt(0)
	v_add_f32_e32 v31, v44, v45
	v_fmamk_f32 v31, v31, 0x3b000000, v221
	v_mul_f32_e32 v42, 0x4f800000, v31
	v_cmp_gt_f32_e32 vcc, s43, v31
	v_and_or_b32 v30, v28, s19, v30
	s_nop 0
	v_cndmask_b32_e32 v42, v31, v42, vcc
	v_sqrt_f32_e32 v44, v42
	v_lshrrev_b32_e32 v31, 16, v43
	v_and_or_b32 v31, v29, s19, v31
	v_add_u32_e32 v28, -1, v44
	v_fma_f32 v29, -v28, v44, v42
	v_cmp_ge_f32_e64 s[6:7], 0, v29
	v_add_u32_e32 v29, 1, v44
	v_fma_f32 v43, -v29, v44, v42
	v_cndmask_b32_e64 v28, v44, v28, s[6:7]
	v_cmp_lt_f32_e64 s[6:7], 0, v43
	s_nop 1
	v_cndmask_b32_e64 v28, v28, v29, s[6:7]
	v_mul_f32_e32 v29, 0x37800000, v28
	v_cndmask_b32_e32 v28, v28, v29, vcc
	v_cmp_class_f32_e32 vcc, v42, v222
	v_and_or_b32 v29, v41, s19, v47
	v_lshlrev_b32_e32 v41, 16, v19
	v_cndmask_b32_e32 v44, v28, v42, vcc
	v_div_scale_f32 v42, s[6:7], v44, v44, 1.0
	v_rcp_f32_e32 v43, v42
	v_and_or_b32 v28, v40, s19, v46
	global_store_dwordx4 v[26:27], v[28:31], off offset:2048
	v_lshlrev_b32_e32 v40, 16, v18
	v_fma_f32 v26, -v42, v43, 1.0
	v_fmac_f32_e32 v43, v26, v43
	v_div_scale_f32 v26, vcc, 1.0, v44, 1.0
	v_mul_f32_e32 v27, v26, v43
	v_fma_f32 v28, -v42, v27, v26
	v_fmac_f32_e32 v27, v28, v43
	v_fma_f32 v26, -v42, v27, v26
	v_div_fmas_f32 v45, v26, v43, v27
	v_lshlrev_b32_e32 v27, 16, v17
	v_lshlrev_b32_e32 v26, 16, v16
	v_and_b32_e32 v29, 0xffff0000, v17
	v_and_b32_e32 v28, 0xffff0000, v16
	v_pk_mul_f32 v[16:17], v[26:27], v[26:27]
	v_pk_mul_f32 v[30:31], v[28:29], v[28:29]
	v_and_b32_e32 v43, 0xffff0000, v19
	v_add_f32_e32 v16, v16, v30
	v_add_f32_e32 v16, v17, v16
	v_add_f32_e32 v16, v31, v16
	v_and_b32_e32 v42, 0xffff0000, v18
	v_mov_b32_e32 v18, v43
	v_mov_b32_e32 v19, v41
	v_fmac_f32_e32 v16, v40, v40
	v_pk_mul_f32 v[18:19], v[18:19], v[18:19]
	v_fmac_f32_e32 v16, v42, v42
	v_add_f32_e32 v16, v19, v16
	v_add_f32_e32 v17, v18, v16
	ds_bpermute_b32 v46, v212, v17
	v_div_fixup_f32 v16, v45, v44, 1.0
	v_pk_mul_f32 v[18:19], v[16:17], v[36:37] op_sel_hi:[0,1]
	v_pk_mul_f32 v[30:31], v[16:17], v[32:33] op_sel_hi:[0,1]
	v_pk_mul_f32 v[32:33], v[16:17], v[38:39] op_sel_hi:[0,1]
	s_waitcnt lgkmcnt(0)
	v_add_f32_e32 v36, v17, v46
	ds_bpermute_b32 v37, v213, v36
	v_pk_mul_f32 v[16:17], v[16:17], v[34:35] op_sel_hi:[0,1]
	v_bfe_u32 v35, v16, 16, 1
	v_add3_u32 v16, v16, v35, s47
	v_bfe_u32 v34, v17, 16, 1
	s_waitcnt lgkmcnt(0)
	v_add_f32_e32 v36, v36, v37
	ds_bpermute_b32 v37, v214, v36
	v_bfe_u32 v38, v31, 16, 1
	v_add3_u32 v31, v31, v38, s47
	v_add3_u32 v17, v17, v34, s47
	v_bfe_u32 v34, v18, 16, 1
	s_waitcnt lgkmcnt(0)
	v_add_f32_e32 v35, v36, v37
	ds_bpermute_b32 v36, v215, v35
	v_bfe_u32 v37, v19, 16, 1
	v_add3_u32 v19, v19, v37, s47
	v_bfe_u32 v38, v32, 16, 1
	v_lshrrev_b32_e32 v37, 16, v19
	s_waitcnt lgkmcnt(0)
	v_add_f32_e32 v35, v35, v36
	ds_bpermute_b32 v36, v197, v35
	v_add3_u32 v32, v32, v38, s47
	v_add3_u32 v18, v18, v34, s47
	v_lshrrev_b32_e32 v34, 16, v18
	v_lshrrev_b32_e32 v18, 16, v32
	s_waitcnt lgkmcnt(0)
	v_add_f32_e32 v35, v35, v36
	ds_bpermute_b32 v36, v149, v35
	v_bfe_u32 v39, v30, 16, 1
	v_add3_u32 v30, v30, v39, s47
	v_bfe_u32 v39, v33, 16, 1
	v_add3_u32 v33, v33, v39, s47
	s_waitcnt lgkmcnt(0)
	v_add_f32_e32 v19, v35, v36
	v_fmamk_f32 v19, v19, 0x3b000000, v221
	v_mul_f32_e32 v32, 0x4f800000, v19
	v_cmp_gt_f32_e32 vcc, s43, v19
	v_and_or_b32 v18, v16, s19, v18
	s_nop 0
	v_cndmask_b32_e32 v32, v19, v32, vcc
	v_sqrt_f32_e32 v35, v32
	v_lshrrev_b32_e32 v19, 16, v33
	v_and_or_b32 v19, v17, s19, v19
	v_add_u32_e32 v16, -1, v35
	v_fma_f32 v17, -v16, v35, v32
	v_cmp_ge_f32_e64 s[6:7], 0, v17
	v_add_u32_e32 v17, 1, v35
	v_fma_f32 v33, -v17, v35, v32
	v_cndmask_b32_e64 v16, v35, v16, s[6:7]
	v_cmp_lt_f32_e64 s[6:7], 0, v33
	v_and_b32_e32 v35, 0xffff0000, v15
	s_nop 0
	v_cndmask_b32_e64 v16, v16, v17, s[6:7]
	v_mul_f32_e32 v17, 0x37800000, v16
	v_cndmask_b32_e32 v16, v16, v17, vcc
	v_cmp_class_f32_e32 vcc, v32, v222
	v_and_or_b32 v17, v31, s19, v37
	s_nop 0
	v_cndmask_b32_e32 v36, v16, v32, vcc
	v_div_scale_f32 v32, s[6:7], v36, v36, 1.0
	v_rcp_f32_e32 v33, v32
	v_and_or_b32 v16, v30, s19, v34
	global_store_dwordx4 v[22:23], v[16:19], off offset:-4096
	v_and_b32_e32 v34, 0xffff0000, v14
	s_nop 0
	v_fma_f32 v16, -v32, v33, 1.0
	v_fmac_f32_e32 v33, v16, v33
	v_div_scale_f32 v16, vcc, 1.0, v36, 1.0
	v_mul_f32_e32 v17, v16, v33
	v_fma_f32 v18, -v32, v17, v16
	v_fmac_f32_e32 v17, v18, v33
	v_fma_f32 v16, -v32, v17, v16
	v_div_fmas_f32 v37, v16, v33, v17
	v_lshlrev_b32_e32 v17, 16, v13
	v_lshlrev_b32_e32 v16, 16, v12
	v_and_b32_e32 v19, 0xffff0000, v13
	v_and_b32_e32 v18, 0xffff0000, v12
	v_pk_mul_f32 v[12:13], v[16:17], v[16:17]
	v_pk_mul_f32 v[30:31], v[18:19], v[18:19]
	v_lshlrev_b32_e32 v33, 16, v15
	v_add_f32_e32 v12, v12, v30
	v_add_f32_e32 v12, v13, v12
	v_lshlrev_b32_e32 v32, 16, v14
	v_add_f32_e32 v12, v31, v12
	v_mov_b32_e32 v14, v35
	v_mov_b32_e32 v15, v33
	v_fmac_f32_e32 v12, v32, v32
	v_pk_mul_f32 v[14:15], v[14:15], v[14:15]
	v_fmac_f32_e32 v12, v34, v34
	v_add_f32_e32 v12, v15, v12
	v_add_f32_e32 v13, v14, v12
	ds_bpermute_b32 v30, v212, v13
	v_div_fixup_f32 v12, v37, v36, 1.0
	v_pk_mul_f32 v[14:15], v[12:13], v[26:27] op_sel_hi:[0,1]
	v_pk_mul_f32 v[26:27], v[12:13], v[28:29] op_sel_hi:[0,1]
	v_pk_mul_f32 v[28:29], v[12:13], v[40:41] op_sel_hi:[0,1]
	s_waitcnt lgkmcnt(0)
	v_add_f32_e32 v30, v13, v30
	ds_bpermute_b32 v31, v213, v30
	v_pk_mul_f32 v[12:13], v[12:13], v[42:43] op_sel_hi:[0,1]
	v_bfe_u32 v37, v12, 16, 1
	v_add3_u32 v12, v12, v37, s47
	v_bfe_u32 v37, v15, 16, 1
	s_waitcnt lgkmcnt(0)
	v_add_f32_e32 v30, v30, v31
	ds_bpermute_b32 v31, v214, v30
	v_bfe_u32 v36, v13, 16, 1
	v_bfe_u32 v38, v27, 16, 1
	v_add3_u32 v15, v15, v37, s47
	v_add3_u32 v27, v27, v38, s47
	s_waitcnt lgkmcnt(0)
	v_add_f32_e32 v30, v30, v31
	ds_bpermute_b32 v31, v215, v30
	v_add3_u32 v13, v13, v36, s47
	v_bfe_u32 v36, v14, 16, 1
	v_bfe_u32 v38, v28, 16, 1
	v_lshrrev_b32_e32 v37, 16, v15
	s_waitcnt lgkmcnt(0)
	v_add_f32_e32 v30, v30, v31
	ds_bpermute_b32 v31, v197, v30
	v_add3_u32 v28, v28, v38, s47
	v_add3_u32 v14, v14, v36, s47
	v_lshrrev_b32_e32 v36, 16, v14
	v_lshrrev_b32_e32 v14, 16, v28
	s_waitcnt lgkmcnt(0)
	v_add_f32_e32 v30, v30, v31
	ds_bpermute_b32 v31, v149, v30
	v_bfe_u32 v39, v26, 16, 1
	v_add3_u32 v26, v26, v39, s47
	v_bfe_u32 v39, v29, 16, 1
	v_add3_u32 v29, v29, v39, s47
	s_waitcnt lgkmcnt(0)
	v_add_f32_e32 v15, v30, v31
	v_fmamk_f32 v15, v15, 0x3b000000, v221
	v_mul_f32_e32 v28, 0x4f800000, v15
	v_cmp_gt_f32_e32 vcc, s43, v15
	v_and_or_b32 v14, v12, s19, v14
	s_nop 0
	v_cndmask_b32_e32 v28, v15, v28, vcc
	v_sqrt_f32_e32 v30, v28
	v_lshrrev_b32_e32 v15, 16, v29
	v_and_or_b32 v15, v13, s19, v15
	v_add_u32_e32 v12, -1, v30
	v_fma_f32 v13, -v12, v30, v28
	v_cmp_ge_f32_e64 s[6:7], 0, v13
	v_add_u32_e32 v13, 1, v30
	v_fma_f32 v29, -v13, v30, v28
	v_cndmask_b32_e64 v12, v30, v12, s[6:7]
	v_cmp_lt_f32_e64 s[6:7], 0, v29
	s_nop 1
	v_cndmask_b32_e64 v12, v12, v13, s[6:7]
	v_mul_f32_e32 v13, 0x37800000, v12
	v_cndmask_b32_e32 v12, v12, v13, vcc
	v_cmp_class_f32_e32 vcc, v28, v222
	v_and_or_b32 v13, v27, s19, v37
	v_lshlrev_b32_e32 v27, 16, v11
	v_cndmask_b32_e32 v30, v12, v28, vcc
	v_div_scale_f32 v28, s[6:7], v30, v30, 1.0
	v_rcp_f32_e32 v29, v28
	v_and_or_b32 v12, v26, s19, v36
	global_store_dwordx4 v[24:25], v[12:15], off offset:2048
	v_lshlrev_b32_e32 v26, 16, v10
	s_nop 0
	v_fma_f32 v12, -v28, v29, 1.0
	v_fmac_f32_e32 v29, v12, v29
	v_div_scale_f32 v12, vcc, 1.0, v30, 1.0
	v_mul_f32_e32 v13, v12, v29
	v_fma_f32 v14, -v28, v13, v12
	v_fmac_f32_e32 v13, v14, v29
	v_fma_f32 v12, -v28, v13, v12
	v_div_fmas_f32 v31, v12, v29, v13
	v_lshlrev_b32_e32 v13, 16, v9
	v_lshlrev_b32_e32 v12, 16, v8
	v_and_b32_e32 v15, 0xffff0000, v9
	v_and_b32_e32 v14, 0xffff0000, v8
	v_pk_mul_f32 v[8:9], v[12:13], v[12:13]
	v_pk_mul_f32 v[24:25], v[14:15], v[14:15]
	v_and_b32_e32 v29, 0xffff0000, v11
	v_add_f32_e32 v8, v8, v24
	v_add_f32_e32 v8, v9, v8
	v_add_f32_e32 v8, v25, v8
	v_and_b32_e32 v28, 0xffff0000, v10
	v_mov_b32_e32 v10, v29
	v_mov_b32_e32 v11, v27
	v_fmac_f32_e32 v8, v26, v26
	v_pk_mul_f32 v[10:11], v[10:11], v[10:11]
	v_fmac_f32_e32 v8, v28, v28
	v_add_f32_e32 v8, v11, v8
	v_add_f32_e32 v9, v10, v8
	ds_bpermute_b32 v24, v212, v9
	v_div_fixup_f32 v8, v31, v30, 1.0
	v_pk_mul_f32 v[10:11], v[8:9], v[16:17] op_sel_hi:[0,1]
	v_pk_mul_f32 v[16:17], v[8:9], v[18:19] op_sel_hi:[0,1]
	v_pk_mul_f32 v[18:19], v[8:9], v[32:33] op_sel_hi:[0,1]
	s_waitcnt lgkmcnt(0)
	v_add_f32_e32 v24, v9, v24
	ds_bpermute_b32 v25, v213, v24
	v_pk_mul_f32 v[8:9], v[8:9], v[34:35] op_sel_hi:[0,1]
	v_bfe_u32 v31, v8, 16, 1
	v_add3_u32 v8, v8, v31, s47
	v_bfe_u32 v31, v11, 16, 1
	s_waitcnt lgkmcnt(0)
	v_add_f32_e32 v24, v24, v25
	ds_bpermute_b32 v25, v214, v24
	v_bfe_u32 v30, v9, 16, 1
	v_bfe_u32 v32, v17, 16, 1
	v_add3_u32 v11, v11, v31, s47
	v_add3_u32 v17, v17, v32, s47
	s_waitcnt lgkmcnt(0)
	v_add_f32_e32 v24, v24, v25
	ds_bpermute_b32 v25, v215, v24
	v_add3_u32 v9, v9, v30, s47
	v_bfe_u32 v30, v10, 16, 1
	v_bfe_u32 v32, v18, 16, 1
	v_lshrrev_b32_e32 v31, 16, v11
	s_waitcnt lgkmcnt(0)
	v_add_f32_e32 v24, v24, v25
	ds_bpermute_b32 v25, v197, v24
	v_add3_u32 v18, v18, v32, s47
	v_add3_u32 v10, v10, v30, s47
	v_lshrrev_b32_e32 v30, 16, v10
	v_lshrrev_b32_e32 v10, 16, v18
	s_waitcnt lgkmcnt(0)
	v_add_f32_e32 v24, v24, v25
	ds_bpermute_b32 v25, v149, v24
	v_bfe_u32 v33, v16, 16, 1
	v_add3_u32 v16, v16, v33, s47
	v_bfe_u32 v33, v19, 16, 1
	v_add3_u32 v19, v19, v33, s47
	s_waitcnt lgkmcnt(0)
	v_add_f32_e32 v11, v24, v25
	v_fmamk_f32 v11, v11, 0x3b000000, v221
	v_mul_f32_e32 v18, 0x4f800000, v11
	v_cmp_gt_f32_e32 vcc, s43, v11
	v_and_or_b32 v10, v8, s19, v10
	v_and_b32_e32 v25, 0xffff0000, v7
	v_cndmask_b32_e32 v18, v11, v18, vcc
	v_sqrt_f32_e32 v24, v18
	v_lshrrev_b32_e32 v11, 16, v19
	v_and_or_b32 v11, v9, s19, v11
	v_add_u32_e32 v8, -1, v24
	v_fma_f32 v9, -v8, v24, v18
	v_cmp_ge_f32_e64 s[6:7], 0, v9
	v_add_u32_e32 v9, 1, v24
	v_fma_f32 v19, -v9, v24, v18
	v_cndmask_b32_e64 v8, v24, v8, s[6:7]
	v_cmp_lt_f32_e64 s[6:7], 0, v19
	v_and_b32_e32 v24, 0xffff0000, v6
	s_nop 0
	v_cndmask_b32_e64 v8, v8, v9, s[6:7]
	v_mul_f32_e32 v9, 0x37800000, v8
	v_cndmask_b32_e32 v8, v8, v9, vcc
	v_cmp_class_f32_e32 vcc, v18, v222
	v_and_or_b32 v9, v17, s19, v31
	s_nop 0
	v_cndmask_b32_e32 v32, v8, v18, vcc
	v_div_scale_f32 v18, s[6:7], v32, v32, 1.0
	v_rcp_f32_e32 v19, v18
	v_and_or_b32 v8, v16, s19, v30
	global_store_dwordx4 v[22:23], v[8:11], off
	s_nop 1
	v_fma_f32 v8, -v18, v19, 1.0
	v_fmac_f32_e32 v19, v8, v19
	v_div_scale_f32 v8, vcc, 1.0, v32, 1.0
	v_mul_f32_e32 v9, v8, v19
	v_fma_f32 v10, -v18, v9, v8
	v_fmac_f32_e32 v9, v10, v19
	v_fma_f32 v8, -v18, v9, v8
	v_div_fmas_f32 v30, v8, v19, v9
	v_lshlrev_b32_e32 v9, 16, v5
	v_lshlrev_b32_e32 v8, 16, v4
	v_and_b32_e32 v11, 0xffff0000, v5
	v_and_b32_e32 v10, 0xffff0000, v4
	v_pk_mul_f32 v[4:5], v[8:9], v[8:9]
	v_pk_mul_f32 v[16:17], v[10:11], v[10:11]
	v_lshlrev_b32_e32 v19, 16, v7
	v_add_f32_e32 v4, v4, v16
	v_add_f32_e32 v4, v5, v4
	v_lshlrev_b32_e32 v18, 16, v6
	v_add_f32_e32 v4, v17, v4
	v_mov_b32_e32 v6, v25
	v_mov_b32_e32 v7, v19
	v_fmac_f32_e32 v4, v18, v18
	v_pk_mul_f32 v[6:7], v[6:7], v[6:7]
	v_fmac_f32_e32 v4, v24, v24
	v_add_f32_e32 v4, v7, v4
	v_add_f32_e32 v5, v6, v4
	ds_bpermute_b32 v16, v212, v5
	v_div_fixup_f32 v4, v30, v32, 1.0
	v_pk_mul_f32 v[6:7], v[4:5], v[12:13] op_sel_hi:[0,1]
	v_pk_mul_f32 v[12:13], v[4:5], v[14:15] op_sel_hi:[0,1]
	v_pk_mul_f32 v[14:15], v[4:5], v[26:27] op_sel_hi:[0,1]
	s_waitcnt lgkmcnt(0)
	v_add_f32_e32 v16, v5, v16
	ds_bpermute_b32 v17, v213, v16
	v_pk_mul_f32 v[4:5], v[4:5], v[28:29] op_sel_hi:[0,1]
	v_bfe_u32 v27, v4, 16, 1
	v_add3_u32 v4, v4, v27, s47
	v_bfe_u32 v27, v7, 16, 1
	s_waitcnt lgkmcnt(0)
	v_add_f32_e32 v16, v16, v17
	ds_bpermute_b32 v17, v214, v16
	v_bfe_u32 v26, v5, 16, 1
	v_bfe_u32 v28, v13, 16, 1
	v_add3_u32 v7, v7, v27, s47
	v_add3_u32 v13, v13, v28, s47
	s_waitcnt lgkmcnt(0)
	v_add_f32_e32 v16, v16, v17
	ds_bpermute_b32 v17, v215, v16
	v_add3_u32 v5, v5, v26, s47
	v_bfe_u32 v26, v6, 16, 1
	v_bfe_u32 v28, v14, 16, 1
	v_lshrrev_b32_e32 v27, 16, v7
	s_waitcnt lgkmcnt(0)
	v_add_f32_e32 v16, v16, v17
	ds_bpermute_b32 v17, v197, v16
	v_add3_u32 v14, v14, v28, s47
	v_add3_u32 v6, v6, v26, s47
	v_lshrrev_b32_e32 v26, 16, v6
	v_lshrrev_b32_e32 v6, 16, v14
	s_waitcnt lgkmcnt(0)
	v_add_f32_e32 v16, v16, v17
	ds_bpermute_b32 v17, v149, v16
	v_bfe_u32 v29, v12, 16, 1
	v_add3_u32 v12, v12, v29, s47
	v_bfe_u32 v29, v15, 16, 1
	v_add3_u32 v15, v15, v29, s47
	s_waitcnt lgkmcnt(0)
	v_add_f32_e32 v7, v16, v17
	v_fmamk_f32 v7, v7, 0x3b000000, v221
	v_mul_f32_e32 v14, 0x4f800000, v7
	v_cmp_gt_f32_e32 vcc, s43, v7
	v_and_or_b32 v6, v4, s19, v6
	s_waitcnt vmcnt(5)
	v_and_b32_e32 v17, 0xffff0000, v3
	v_cndmask_b32_e32 v14, v7, v14, vcc
	v_sqrt_f32_e32 v16, v14
	v_lshrrev_b32_e32 v7, 16, v15
	v_and_or_b32 v7, v5, s19, v7
	v_add_u32_e32 v4, -1, v16
	v_fma_f32 v5, -v4, v16, v14
	v_cmp_ge_f32_e64 s[6:7], 0, v5
	v_add_u32_e32 v5, 1, v16
	v_fma_f32 v15, -v5, v16, v14
	v_cndmask_b32_e64 v4, v16, v4, s[6:7]
	v_cmp_lt_f32_e64 s[6:7], 0, v15
	v_and_b32_e32 v16, 0xffff0000, v2
	s_nop 0
	v_cndmask_b32_e64 v4, v4, v5, s[6:7]
	v_mul_f32_e32 v5, 0x37800000, v4
	v_cndmask_b32_e32 v4, v4, v5, vcc
	v_cmp_class_f32_e32 vcc, v14, v222
	v_and_or_b32 v5, v13, s19, v27
	s_nop 0
	v_cndmask_b32_e32 v28, v4, v14, vcc
	v_div_scale_f32 v14, s[6:7], v28, v28, 1.0
	v_rcp_f32_e32 v15, v14
	v_and_or_b32 v4, v12, s19, v26
	global_store_dwordx4 v[22:23], v[4:7], off offset:2048
	s_nop 1
	v_fma_f32 v4, -v14, v15, 1.0
	v_fmac_f32_e32 v15, v4, v15
	v_div_scale_f32 v4, vcc, 1.0, v28, 1.0
	v_mul_f32_e32 v5, v4, v15
	v_fma_f32 v6, -v14, v5, v4
	v_fmac_f32_e32 v5, v6, v15
	v_fma_f32 v4, -v14, v5, v4
	v_div_fmas_f32 v22, v4, v15, v5
	v_lshlrev_b32_e32 v5, 16, v1
	v_lshlrev_b32_e32 v4, 16, v0
	v_and_b32_e32 v7, 0xffff0000, v1
	v_and_b32_e32 v6, 0xffff0000, v0
	v_pk_mul_f32 v[0:1], v[4:5], v[4:5]
	v_pk_mul_f32 v[12:13], v[6:7], v[6:7]
	v_lshlrev_b32_e32 v15, 16, v3
	v_add_f32_e32 v0, v0, v12
	v_add_f32_e32 v0, v1, v0
	v_lshlrev_b32_e32 v14, 16, v2
	v_add_f32_e32 v0, v13, v0
	v_mov_b32_e32 v2, v17
	v_mov_b32_e32 v3, v15
	v_fmac_f32_e32 v0, v14, v14
	v_pk_mul_f32 v[2:3], v[2:3], v[2:3]
	v_fmac_f32_e32 v0, v16, v16
	v_add_f32_e32 v0, v3, v0
	v_add_f32_e32 v1, v2, v0
	ds_bpermute_b32 v12, v212, v1
	v_div_fixup_f32 v0, v22, v28, 1.0
	v_pk_mul_f32 v[2:3], v[0:1], v[8:9] op_sel_hi:[0,1]
	v_pk_mul_f32 v[8:9], v[0:1], v[10:11] op_sel_hi:[0,1]
	v_pk_mul_f32 v[10:11], v[0:1], v[18:19] op_sel_hi:[0,1]
	s_waitcnt lgkmcnt(0)
	v_add_f32_e32 v12, v1, v12
	ds_bpermute_b32 v13, v213, v12
	v_pk_mul_f32 v[0:1], v[0:1], v[24:25] op_sel_hi:[0,1]
	v_bfe_u32 v19, v0, 16, 1
	v_add3_u32 v0, v0, v19, s47
	v_bfe_u32 v19, v3, 16, 1
	s_waitcnt lgkmcnt(0)
	v_add_f32_e32 v12, v12, v13
	ds_bpermute_b32 v13, v214, v12
	v_bfe_u32 v18, v1, 16, 1
	v_bfe_u32 v22, v9, 16, 1
	v_add3_u32 v3, v3, v19, s47
	v_add3_u32 v9, v9, v22, s47
	s_waitcnt lgkmcnt(0)
	v_add_f32_e32 v12, v12, v13
	ds_bpermute_b32 v13, v215, v12
	v_add3_u32 v1, v1, v18, s47
	v_bfe_u32 v18, v2, 16, 1
	v_bfe_u32 v22, v10, 16, 1
	v_lshrrev_b32_e32 v19, 16, v3
	s_waitcnt lgkmcnt(0)
	v_add_f32_e32 v12, v12, v13
	ds_bpermute_b32 v13, v197, v12
	v_add3_u32 v10, v10, v22, s47
	v_add3_u32 v2, v2, v18, s47
	v_lshrrev_b32_e32 v18, 16, v2
	v_lshrrev_b32_e32 v2, 16, v10
	s_waitcnt lgkmcnt(0)
	v_add_f32_e32 v12, v12, v13
	ds_bpermute_b32 v13, v149, v12
	v_bfe_u32 v23, v8, 16, 1
	v_add3_u32 v8, v8, v23, s47
	v_bfe_u32 v23, v11, 16, 1
	v_add3_u32 v11, v11, v23, s47
	s_waitcnt lgkmcnt(0)
	v_add_f32_e32 v3, v12, v13
	v_fmamk_f32 v3, v3, 0x3b000000, v221
	v_mul_f32_e32 v10, 0x4f800000, v3
	v_cmp_gt_f32_e32 vcc, s43, v3
	v_and_or_b32 v2, v0, s19, v2
	s_nop 0
	v_cndmask_b32_e32 v10, v3, v10, vcc
	v_sqrt_f32_e32 v12, v10
	v_lshrrev_b32_e32 v3, 16, v11
	v_and_or_b32 v3, v1, s19, v3
	v_add_u32_e32 v0, -1, v12
	v_fma_f32 v1, -v0, v12, v10
	v_cmp_ge_f32_e64 s[6:7], 0, v1
	v_add_u32_e32 v1, 1, v12
	v_fma_f32 v11, -v1, v12, v10
	v_cndmask_b32_e64 v0, v12, v0, s[6:7]
	v_cmp_lt_f32_e64 s[6:7], 0, v11
	s_nop 1
	v_cndmask_b32_e64 v0, v0, v1, s[6:7]
	v_mul_f32_e32 v1, 0x37800000, v0
	v_cndmask_b32_e32 v0, v0, v1, vcc
	v_cmp_class_f32_e32 vcc, v10, v222
	v_and_or_b32 v1, v9, s19, v19
	s_nop 0
	v_cndmask_b32_e32 v10, v0, v10, vcc
	v_div_scale_f32 v11, s[6:7], v10, v10, 1.0
	v_rcp_f32_e32 v12, v11
	v_and_or_b32 v0, v8, s19, v18
	global_store_dwordx4 v[20:21], v[0:3], off
	s_nop 1
	v_fma_f32 v0, -v11, v12, 1.0
	v_fmac_f32_e32 v12, v0, v12
	v_div_scale_f32 v0, vcc, 1.0, v10, 1.0
	v_mul_f32_e32 v1, v0, v12
	v_fma_f32 v2, -v11, v1, v0
	v_fmac_f32_e32 v1, v2, v12
	v_fma_f32 v0, -v11, v1, v0
	v_div_fmas_f32 v0, v0, v12, v1
	v_div_fixup_f32 v0, v0, v10, 1.0
	v_pk_mul_f32 v[2:3], v[0:1], v[4:5] op_sel_hi:[0,1]
	v_pk_mul_f32 v[4:5], v[0:1], v[6:7] op_sel_hi:[0,1]
	v_pk_mul_f32 v[6:7], v[0:1], v[14:15] op_sel_hi:[0,1]
	v_pk_mul_f32 v[0:1], v[0:1], v[16:17] op_sel_hi:[0,1]
	v_bfe_u32 v8, v1, 16, 1
	v_bfe_u32 v9, v0, 16, 1
	v_bfe_u32 v10, v5, 16, 1
	v_bfe_u32 v11, v4, 16, 1
	v_add3_u32 v4, v4, v11, s47
	v_add3_u32 v5, v5, v10, s47
	v_add3_u32 v0, v0, v9, s47
	v_add3_u32 v1, v1, v8, s47
	v_bfe_u32 v8, v2, 16, 1
	v_bfe_u32 v9, v3, 16, 1
	v_bfe_u32 v10, v6, 16, 1
	v_bfe_u32 v11, v7, 16, 1
	v_add3_u32 v7, v7, v11, s47
	v_add3_u32 v6, v6, v10, s47
	v_add3_u32 v3, v3, v9, s47
	v_add3_u32 v2, v2, v8, s47
	v_lshrrev_b32_e32 v8, 16, v2
	v_lshrrev_b32_e32 v9, 16, v3
	v_lshrrev_b32_e32 v2, 16, v6
	v_lshrrev_b32_e32 v3, 16, v7
	v_and_or_b32 v3, v1, s19, v3
	v_and_or_b32 v2, v0, s19, v2
	v_and_or_b32 v1, v5, s19, v9
	v_and_or_b32 v0, v4, s19, v8
	global_store_dwordx4 v[20:21], v[0:3], off offset:2048
	s_barrier
	s_cbranch_scc0 .LBB0_422
